# MoBA sel work queue: next unit id fetched (atomic) during the current unit instead of at the serialized loop head
# baseline (speedup 1.0000x reference)
; #define LAS __attribute__((address_space(3)))
; DI void phase_moba_sel(const Args& A, unsigned char* lds, LAS unsigned char* lds3, int tid, int wid, int lane) {
;     const bf16_t* QKV = (const bf16_t*)(A.ws + WS_QKV); const unsigned* SEL = (const unsigned*)(A.ws + WS_SEL);
;     bf16_t* PO = (bf16_t*)(A.ws + WS_PO); float* PML = (float*)(A.ws + WS_PML);
;     unsigned* ctr = (unsigned*)(A.ws + WS_CTL) + 64;
;     volatile int* misc = (volatile int*)(lds + MB_MISC);
;     unsigned short* list = (unsigned short*)(lds + MB_LIST);
;     const int r32 = lane & 31, hi = lane >> 5;
;     for (;;) {
;         __syncthreads();
;         if (tid == 0) { misc[0] = (int)atomicAdd(ctr, 1u); misc[1] = 0; }
;         __syncthreads();
;         const int u = misc[0];
;         if (u >= 63 * 32) break;
;         const int j = u >> 5, bh = u & 31, b = bh >> 4, h = bh & 15;
;         moba_stage_kv(QKV, lds, b, h, j, tid);
;         const unsigned* selp = SEL + (size_t)bh * SEQ;
;         for (int s0 = (j + 1) * 256 + tid; s0 < SEQ; s0 += 8 * NTHR) {
.LBB0_1227:
	s_cmp_gt_i32 s40, 10
	s_cselect_b64 s[4:5], -1, 0
	s_cmp_lt_i32 s41, 11
	s_cselect_b64 s[6:7], -1, 0
	s_or_b64 s[10:11], s[4:5], s[6:7]
	s_and_b64 vcc, exec, s[10:11]
	s_cbranch_vccnz .LBB0_1315
	s_mov_b64 s[4:5], s[0:1]
	s_load_dwordx2 s[12:13], s[4:5], 0xa8
	v_mov_b32_e32 v3, v184
	s_mov_b64 s[8:9], src_shared_base
	s_movk_i32 s8, 0xc00
	v_add_u32_e32 v6, 0x200, v3
	v_add_u32_e32 v8, 0x400, v3
	s_waitcnt lgkmcnt(0)
	v_add_u32_e32 v10, 0x600, v3
	v_readfirstlane_b32 s3, v3
	v_ashrrev_i32_e32 v0, 3, v3
	v_ashrrev_i32_e32 v12, 3, v6
	v_ashrrev_i32_e32 v15, 3, v8
	v_ashrrev_i32_e32 v17, 3, v10
	s_ashr_i32 s3, s3, 6
	v_mad_i64_i32 v[4:5], s[6:7], v0, s8, 0
	v_mad_i64_i32 v[6:7], s[6:7], v12, s8, 0
	v_mad_i64_i32 v[8:9], s[6:7], v15, s8, 0
	v_mad_i64_i32 v[10:11], s[6:7], v17, s8, 0
	v_lshlrev_b32_e32 v20, 4, v3
	s_add_u32 s14, s12, 0x4000000
	v_bfe_u32 v16, v3, 5, 1
	v_lshlrev_b32_e32 v19, 12, v3
	v_and_b32_e32 v21, 48, v20
	s_movk_i32 s33, 0x4000
	s_movk_i32 s6, 0x90
	s_addc_u32 s15, s13, 0
	v_mov_b32_e32 v1, 0
	v_and_or_b32 v19, v19, s33, v21
	v_mul_lo_u32 v21, v0, s6
	v_lshlrev_b32_e32 v22, 6, v0
	v_lshlrev_b32_e32 v0, 4, v16
	v_lshl_add_u64 v[98:99], s[14:15], 0, v[0:1]
	v_lshlrev_b32_e32 v0, 1, v3
	v_and_b32_e32 v28, 32, v0
	v_and_b32_e32 v0, 32, v3
	v_and_b32_e32 v126, 31, v3
	v_lshlrev_b32_e32 v14, 3, v3
	v_lshlrev_b32_e32 v0, 1, v0
	v_and_b32_e32 v2, 56, v14
	v_mul_lo_u32 v25, v15, s6
	v_lshlrev_b32_e32 v26, 6, v15
	v_and_b32_e32 v29, 24, v14
	v_lshl_add_u64 v[14:15], s[12:13], 0, v[0:1]
	v_mul_u32_u24_e32 v0, 0x90, v126
	s_movk_i32 s8, 0xff10
	v_mad_i32_i24 v133, v16, s8, v0
	v_mbcnt_lo_u32_b32 v0, -1, 0
	v_and_b32_e32 v18, 7, v3
	v_mbcnt_hi_u32_b32 v143, -1, v0
	v_and_b32_e32 v13, 63, v3
	s_add_u32 s16, s12, 0x3100000
	v_lshlrev_b32_e32 v18, 4, v18
	v_mul_lo_u32 v23, v12, s6
	v_lshlrev_b32_e32 v24, 6, v12
	v_mul_lo_u32 v27, v17, s6
	v_lshlrev_b32_e32 v17, 6, v17
	v_lshlrev_b32_e32 v12, 3, v16
	v_and_b32_e32 v20, 0xc0, v20
	s_mov_b64 s[6:7], 0x14000000
	v_and_b32_e32 v0, 64, v143
	s_addc_u32 s17, s13, 0
	v_cmp_eq_u32_e64 s[4:5], 0, v3
	v_add_u32_e32 v127, 0x100, v3
	v_lshl_or_b32 v128, s3, 5, v126
	v_lshlrev_b32_e32 v129, 8, v16
	v_lshl_add_u64 v[100:101], v[14:15], 0, s[6:7]
	v_cmp_gt_u32_e64 s[6:7], 32, v13
	v_add_u32_e32 v130, 0xfffff100, v3
	v_lshlrev_b32_e32 v131, 2, v3
	v_or3_b32 v132, v20, v28, v29
	s_mov_b64 s[18:19], 0
	v_mov_b32_e32 v102, 0x19000
	v_mov_b32_e32 v105, s9
	v_mov_b32_e32 v104, 0x19000
	s_movk_i32 s36, 0x7e0
	s_movk_i32 s37, 0x1800
	v_lshlrev_b32_e32 v106, 1, v2
	s_mov_b64 s[20:21], 0x1000
	v_lshlrev_b64 v[108:109], 1, v[4:5]
	v_lshlrev_b64 v[110:111], 1, v[6:7]
	v_lshlrev_b64 v[112:113], 1, v[8:9]
	v_lshlrev_b64 v[114:115], 1, v[10:11]
	v_add_u32_e32 v134, v18, v21
	v_add_u32_e32 v135, v19, v22
	v_add_u32_e32 v136, v18, v23
	v_add_u32_e32 v137, v19, v24
	v_add_u32_e32 v138, v18, v25
	v_add_u32_e32 v139, v19, v26
	v_add_u32_e32 v140, v18, v27
	v_add_u32_e32 v141, v19, v17
	s_movk_i32 s42, 0x3e00
	s_movk_i32 s43, 0x3c00
	s_movk_i32 s44, 0x3a00
	s_movk_i32 s45, 0x3800
	s_movk_i32 s46, 0x3600
	s_movk_i32 s47, 0x3400
	s_movk_i32 s48, 0x3200
	v_mov_b32_e32 v116, 0x19004
	s_movk_i32 s49, 0x2fff
	v_lshlrev_b32_e32 v118, 1, v12
	s_mov_b32 s50, 0x3e38aa3b
	v_mov_b32_e32 v142, 0x11000
	v_xor_b32_e32 v144, 32, v143
	v_add_u32_e32 v145, 64, v0
	s_mov_b32 s88, 0
	s_branch .LBB0_1232

; DI void phase_moba_sel(const Args& A, unsigned char* lds, LAS unsigned char* lds3, int tid, int wid, int lane) {
;     ...
;     for (;;) {
;         __syncthreads();
;         if (tid == 0) { misc[0] = (int)atomicAdd(ctr, 1u); misc[1] = 0; }
;         __syncthreads();
;         const int u = misc[0];
;         if (u >= 63 * 32) break;
.LBB0_1232:
	s_barrier
	s_and_saveexec_b64 s[8:9], s[4:5]
	s_cbranch_execz .LBB0_1236
	s_mov_b64 s[24:25], exec
	s_waitcnt lgkmcnt(0)
	v_mbcnt_lo_u32_b32 v0, s24, 0
	v_mbcnt_hi_u32_b32 v0, s25, v0
	v_cmp_eq_u32_e32 vcc, 0, v0
	s_and_saveexec_b64 s[22:23], vcc
	s_cbranch_execz .LBB0_1235
	s_bcnt1_i32_b64 s24, s[24:25]
	v_mov_b32_e32 v2, s24
	s_cmp_eq_u32 s88, 0
	s_cbranch_scc0 .Lsel_havepf
	global_atomic_add v2, v1, v2, s[12:13] offset:256 sc0
	s_branch .LBB0_1235
.Lsel_havepf:
	s_waitcnt vmcnt(0)
	v_mov_b32_e32 v2, v250

; DI void moba_stage_kv(const bf16_t* QKV, unsigned char* lds, int b, int h, int blk, int tid) {
;     const bf16_t* kb = QKV + ((size_t)b * SEQ + blk * 256) * QKVW + 1024 + h * 64;
;     const bf16_t* vb = QKV + ((size_t)b * SEQ + blk * 256) * QKVW + 2048 + h * 64;
;     u32x4 kr[4], vr[4];
; #pragma unroll
;     for (int i = 0; i < 4; ++i) { const int id = tid + 512 * i, key = id >> 3, ch = id & 7; kr[i] = *(const u32x4*)(kb + (size_t)key * QKVW + ch * 8); vr[i] = *(const u32x4*)(vb + (size_t)key * QKVW + ch * 8); }
; #pragma unroll
;     for (int i = 0; i < 4; ++i) { const int id = tid + 512 * i, key = id >> 3, ch = id & 7; *(u32x4*)(lds + MB_K + key * 144 + ch * 16) = kr[i]; *(u32x4*)(lds + MB_V + (ch >> 2) * 16384 + key * 64 + (ch & 3) * 16) = vr[i]; }
; }
; DI void phase_moba_sel(const Args& A, unsigned char* lds, LAS unsigned char* lds3, int tid, int wid, int lane) {
;     ...
;         const int u = misc[0];
;         if (u >= 63 * 32) break;
;         const int j = u >> 5, bh = u & 31, b = bh >> 4, h = bh & 15;
;         moba_stage_kv(QKV, lds, b, h, j, tid);
;         const unsigned* selp = SEL + (size_t)bh * SEQ;
;         for (int s0 = (j + 1) * 256 + tid; s0 < SEQ; s0 += 8 * NTHR) {
.LBB0_1236:
	s_or_b64 exec, exec, s[8:9]
	s_waitcnt lgkmcnt(0)
	s_barrier
	flat_load_dword v0, v[104:105] sc0 sc1
	s_waitcnt vmcnt(0)
	s_mov_b64 s[8:9], -1
	s_waitcnt lgkmcnt(0)
	v_cmp_gt_i32_e32 vcc, s36, v0
	s_and_saveexec_b64 s[22:23], vcc
	s_cbranch_execz .LBB0_1231
	v_ashrrev_i32_e32 v9, 5, v0
	v_lshlrev_b32_e32 v2, 10, v0
	v_lshlrev_b32_e32 v4, 8, v9
	v_and_b32_e32 v120, 0x4000, v2
	v_mov_b32_e32 v121, v1
	v_ashrrev_i32_e32 v5, 31, v4
	v_lshl_add_u64 v[2:3], v[120:121], 0, v[4:5]
	v_mov_b64_e32 v[6:7], s[14:15]
	v_mad_u64_u32 v[6:7], s[8:9], v2, s37, v[6:7]
	v_lshlrev_b32_e32 v2, 6, v0
	v_and_b32_e32 v2, 0x3c0, v2
	v_mad_i32_i24 v7, v3, s37, v7
	v_lshlrev_b32_e32 v2, 1, v2
	v_mov_b32_e32 v3, v1
	v_lshl_add_u64 v[6:7], v[6:7], 0, v[2:3]
	v_mov_b32_e32 v107, v1
	v_lshl_add_u64 v[6:7], v[6:7], 0, v[106:107]
	v_lshl_add_u64 v[34:35], v[6:7], 0, s[20:21]
	v_lshl_add_u64 v[18:19], v[6:7], 0, v[108:109]
	v_lshl_add_u64 v[20:21], v[34:35], 0, v[108:109]
	v_lshl_add_u64 v[26:27], v[6:7], 0, v[110:111]
	v_lshl_add_u64 v[28:29], v[34:35], 0, v[110:111]
	v_lshl_add_u64 v[36:37], v[6:7], 0, v[112:113]
	v_lshl_add_u64 v[38:39], v[34:35], 0, v[112:113]
	v_lshl_add_u64 v[6:7], v[6:7], 0, v[114:115]
	global_load_dwordx4 v[10:13], v[18:19], off offset:2048
	global_load_dwordx4 v[14:17], v[20:21], off
	s_nop 0
	global_load_dwordx4 v[18:21], v[26:27], off offset:2048
	global_load_dwordx4 v[22:25], v[28:29], off
	s_nop 0
	global_load_dwordx4 v[26:29], v[36:37], off offset:2048
	global_load_dwordx4 v[30:33], v[38:39], off
	v_lshl_add_u64 v[42:43], v[34:35], 0, v[114:115]
	global_load_dwordx4 v[34:37], v[6:7], off offset:2048
	global_load_dwordx4 v[38:41], v[42:43], off
	v_add_u32_e32 v6, v127, v4
	v_and_b32_e32 v8, 31, v0
	v_cmp_gt_i32_e32 vcc, s33, v6
	s_waitcnt vmcnt(7)
	ds_write_b128 v134, v[10:13]
	s_waitcnt vmcnt(6)
	ds_write_b128 v135, v[14:17] offset:36864
	s_waitcnt vmcnt(5)
	ds_write_b128 v136, v[18:21]
	s_waitcnt vmcnt(4)
	ds_write_b128 v137, v[22:25] offset:36864
	s_waitcnt vmcnt(3)
	ds_write_b128 v138, v[26:29]
	s_waitcnt vmcnt(2)
	ds_write_b128 v139, v[30:33] offset:36864
	s_waitcnt vmcnt(1)
	ds_write_b128 v140, v[34:37]
	s_waitcnt vmcnt(0)
	ds_write_b128 v141, v[38:41] offset:36864
	s_mov_b64 s[90:91], exec
	s_and_b64 exec, exec, s[4:5]
	s_cbranch_execz .Lsel_nopf
	v_mov_b32_e32 v250, 1
	global_atomic_add v250, v1, v250, s[12:13] offset:256 sc0
	s_mov_b32 s88, 1
.Lsel_nopf:
	s_mov_b64 exec, s[90:91]
	s_and_saveexec_b64 s[8:9], vcc
	s_cbranch_execz .LBB0_1302
	v_add_u32_e32 v3, v130, v4
	v_lshlrev_b32_e32 v4, 16, v8
	v_mov_b32_e32 v5, v1
	v_ashrrev_i32_e32 v7, 31, v6
	v_lshl_add_u64 v[4:5], v[6:7], 2, v[4:5]
	v_lshl_add_u32 v0, v9, 10, v131
	v_lshl_add_u64 v[4:5], s[12:13], 0, v[4:5]
	s_mov_b64 s[24:25], 0
	s_mov_b64 s[26:27], 0
	s_branch .LBB0_1241
